# v13: v8 + attention-B main loop: 32 serialized predicated LUT reads -> batched ds_read2 + exec-masked adds
# speedup vs baseline: 1.0052x; 1.0052x over previous
; #define SBAR() __builtin_amdgcn_sched_barrier(0)
; #define SWRITE(b, i) do { *(bf16x8*)(V_lds + (b) * (int)SHM_V + vst0) = sr_[i].vs0; *(bf16x8*)(V_lds + (b) * (int)SHM_V + vst0 + 8192) = sr_[i].vs1; } while (0)
; #define SWAIT() asm volatile("s_waitcnt vmcnt(0)" ::: "memory")
; #define QK(P0, P1, KS, t) do { float v_ = -A.mshift; if (MODE == 0) { const int z_ = zone_of(t); v_ += (z_ == 0 ? A.farL : (z_ == 2 ? A.farR : 0.f)); } \
;     qkt(P0, P1, KS, qr, v_, r32, hi, half); } while (0)
; template <int MODE>
; __device__ __forceinline__ void attn_unit(const UnitArgs& A, char* lds, const int wave_) {
;     ...
;             const int kr = A.tile0 + t, rq = A.q0 + (qb >> 1);
;             int rs = rq - 4; rs = rs < 0 ? 0 : rs; rs = rs > A.R - 8 ? A.R - 8 : rs;
;             if (kr < rs || kr >= rs + 8) {
; #pragma unroll
;                 for (int r = 0; r < 16; ++r) { p0[r] = NEG; p1[r] = NEG; }
;     ...
;     for (int j = 1; j + 1 < NT; j += 2) {
;         SBAR(); QK(pB0, pB1, K_lds + SHM_K, j);
;         finishSM(pA0, pA1, l_reg, pa0, pa1, pa2, pa3); SBAR();
;         SLOAD(0, j + 1); SBAR();
;         post(pB0, pB1, j); PV(0, pB0, pB1);
;         __syncthreads(); SWAIT(); SWRITE(0, 0);
;         __syncthreads();
;         SBAR(); QK(pA0, pA1, K_lds, j + 1);
;         finishSM(pB0, pB1, l_reg, pa0, pa1, pa2, pa3); SBAR();
;         SLOAD(0, j + 2); SBAR();
.LBB0_422:
	ds_read_b128 v[32:35], v113 offset:49152
	ds_read_b128 v[96:99], v113 offset:57344
	ds_read_b128 v[100:103], v114 offset:49152
	ds_read_b128 v[186:189], v114 offset:57344
	v_readlane_b32 s72, v255, 10
	v_readlane_b32 s73, v255, 11
	v_readlane_b32 s74, v255, 12
	v_readlane_b32 s75, v255, 13
	v_readlane_b32 s76, v255, 14
	v_readlane_b32 s77, v255, 15
	v_readlane_b32 s78, v255, 16
	v_readlane_b32 s79, v255, 17
	v_readlane_b32 s80, v255, 18
	v_readlane_b32 s81, v255, 19
	v_readlane_b32 s82, v255, 20
	v_readlane_b32 s83, v255, 21
	v_readlane_b32 s84, v255, 22
	v_readlane_b32 s85, v255, 23
	v_readlane_b32 s86, v255, 24
	v_readlane_b32 s87, v255, 25
	v_mov_b64_e32 v[64:65], s[72:73]
	v_mov_b64_e32 v[66:67], s[74:75]
	v_mov_b64_e32 v[68:69], s[76:77]
	v_mov_b64_e32 v[70:71], s[78:79]
	v_mov_b64_e32 v[72:73], s[80:81]
	v_mov_b64_e32 v[74:75], s[82:83]
	v_mov_b64_e32 v[76:77], s[84:85]
	v_mov_b64_e32 v[78:79], s[86:87]
	s_waitcnt lgkmcnt(3)
	s_nop 0
	v_mfma_f32_32x32x16_bf16 v[48:63], v[32:35], v[92:95], v[64:79]
	s_waitcnt lgkmcnt(2)
	v_mfma_f32_32x32x16_bf16 v[32:47], v[96:99], v[92:95], v[64:79]
	s_nop 6
	ds_read_b128 v[64:67], v115 offset:49152
	ds_read_b128 v[68:71], v115 offset:57344
	s_waitcnt lgkmcnt(3)
	v_mfma_f32_32x32x16_bf16 v[48:63], v[100:103], v[88:91], v[48:63]
	ds_read_b128 v[72:75], v116 offset:49152
	ds_read_b128 v[76:79], v116 offset:57344
	s_waitcnt lgkmcnt(4)
	v_mfma_f32_32x32x16_bf16 v[32:47], v[186:189], v[88:91], v[32:47]
	s_waitcnt lgkmcnt(3)
	v_mfma_f32_32x32x16_bf16 v[48:63], v[64:67], v[84:87], v[48:63]
	v_cvt_pk_bf16_f32 v64, v117, v118
	v_cvt_pk_bf16_f32 v65, v119, v120
	v_cvt_pk_bf16_f32 v66, v121, v122
	v_cvt_pk_bf16_f32 v67, v123, v124
	v_cvt_pk_bf16_f32 v96, v134, v135
	v_cvt_pk_bf16_f32 v97, v136, v137
	v_cvt_pk_bf16_f32 v98, v138, v139
	s_waitcnt lgkmcnt(2)
	v_mfma_f32_32x32x16_bf16 v[32:47], v[68:71], v[84:87], v[32:47]
	v_cvt_pk_bf16_f32 v99, v140, v141
	v_cvt_pk_bf16_f32 v100, v142, v143
	v_cvt_pk_bf16_f32 v101, v152, v153
	v_cvt_pk_bf16_f32 v102, v154, v155
	v_cvt_pk_bf16_f32 v103, v156, v157
	v_permlane32_swap_b32_e32 v64, v66
	s_waitcnt lgkmcnt(1)
	v_mfma_f32_32x32x16_bf16 v[48:63], v[72:75], v[80:83], v[48:63]
	v_permlane32_swap_b32_e32 v65, v67
	v_permlane32_swap_b32_e32 v96, v98
	v_permlane32_swap_b32_e32 v97, v99
	v_permlane32_swap_b32_e32 v100, v102
	s_waitcnt lgkmcnt(0)
	v_mfma_f32_32x32x16_bf16 v[32:47], v[76:79], v[80:83], v[32:47]
	v_cvt_pk_bf16_f32 v76, v125, v126
	v_cvt_pk_bf16_f32 v77, v127, v128
	v_cvt_pk_bf16_f32 v78, v129, v130
	v_cvt_pk_bf16_f32 v79, v131, v132
	s_nop 0
	v_permlane32_swap_b32_e32 v76, v78
	v_permlane32_swap_b32_e32 v77, v79
	v_permlane32_swap_b32_e32 v101, v103
	s_add_i32 s1, s88, s97
	s_add_i32 s0, s1, 2
	s_min_i32 s72, s0, s71
	s_lshl_b32 s73, s72, 6
	s_mul_i32 s74, s72, 0x50000
	s_mul_hi_i32 s75, s73, 0x1400
	s_add_u32 s72, s33, s74
	s_addc_u32 s73, s92, s75
	s_add_u32 s74, s89, s74
	s_addc_u32 s75, s2, s75
	v_lshl_add_u64 v[68:69], s[74:75], 0, v[144:145]
	v_add_co_u32_e32 v72, vcc, vcc_lo, v68
	s_and_b32 s74, s96, 0x4000
	s_nop 0
	v_addc_co_u32_e32 v73, vcc, 0, v69, vcc
	global_load_dwordx4 v[68:71], v[68:69], off
	s_nop 0
	global_load_dwordx4 v[72:75], v[72:73], off
	v_lshl_add_u64 v[180:181], s[72:73], 0, v[104:105]
	s_mov_b64 s[72:73], 0xe00
	s_add_i32 s74, s74, s70
	v_lshl_add_u64 v[182:183], v[180:181], 0, s[72:73]
	s_mov_b32 s72, m0
	s_mov_b32 m0, s74
	s_nop 0
	global_load_lds_dwordx4 v[182:183], off
	s_mov_b32 m0, s72
	s_mov_b64 s[72:73], 0x28e00
	v_lshl_add_u64 v[180:181], v[180:181], 0, s[72:73]
	s_addk_i32 s74, 0x2000
	s_mov_b32 s72, m0
	s_mov_b32 m0, s74
	s_nop 0
	global_load_lds_dwordx4 v[180:181], off
	s_mov_b32 m0, s72
	s_add_i32 s74, s1, 1
	s_cmp_ge_u32 s74, s3
	s_cselect_b64 s[72:73], -1, 0
	s_cmp_lt_u32 s74, s91
	s_cselect_b64 s[74:75], -1, 0
	s_and_b64 s[72:73], s[72:73], s[74:75]
	v_mov_b32_e32 v197, 0xf149f2ca
	s_andn2_b64 vcc, exec, s[72:73]
	v_mov_b32_e32 v196, 0xf149f2ca
	v_mov_b32_e32 v195, 0xf149f2ca
	v_mov_b32_e32 v194, 0xf149f2ca
	v_mov_b32_e32 v193, 0xf149f2ca
	v_mov_b32_e32 v192, 0xf149f2ca
	v_mov_b32_e32 v191, 0xf149f2ca
	v_mov_b32_e32 v190, 0xf149f2ca
	v_mov_b32_e32 v189, 0xf149f2ca
	v_mov_b32_e32 v188, 0xf149f2ca
	v_mov_b32_e32 v187, 0xf149f2ca
	v_mov_b32_e32 v186, 0xf149f2ca
	v_mov_b32_e32 v185, 0xf149f2ca
	v_mov_b32_e32 v181, 0xf149f2ca
	v_mov_b32_e32 v180, 0xf149f2ca
	v_mov_b32_e32 v179, 0xf149f2ca
	v_mov_b32_e32 v212, 0xf149f2ca
	v_mov_b32_e32 v211, 0xf149f2ca
	v_mov_b32_e32 v210, 0xf149f2ca
	v_mov_b32_e32 v209, 0xf149f2ca
	v_mov_b32_e32 v208, 0xf149f2ca
	v_mov_b32_e32 v207, 0xf149f2ca
	v_mov_b32_e32 v206, 0xf149f2ca
	v_mov_b32_e32 v205, 0xf149f2ca
	v_mov_b32_e32 v204, 0xf149f2ca
	v_mov_b32_e32 v203, 0xf149f2ca
	v_mov_b32_e32 v202, 0xf149f2ca
	v_mov_b32_e32 v201, 0xf149f2ca
	v_mov_b32_e32 v200, 0xf149f2ca
	v_mov_b32_e32 v199, 0xf149f2ca
	v_mov_b32_e32 v198, 0xf149f2ca
	v_mov_b32_e32 v213, 0xf149f2ca
	s_cbranch_vccnz .LBB0_488
; #define SBAR() __builtin_amdgcn_sched_barrier(0)
; #define PVLOAD(D0, X) do { X[0] = tr_read<v_rd_off(D0, 0, 0)>(vb); X[1] = tr_read<v_rd_off(D0, 0, 1)>(vb); X[2] = tr_read<v_rd_off(D0, 1, 0)>(vb); X[3] = tr_read<v_rd_off(D0, 1, 1)>(vb); \
;     X[4] = tr_read<v_rd_off(D0, 2, 0)>(vb); X[5] = tr_read<v_rd_off(D0, 2, 1)>(vb); X[6] = tr_read<v_rd_off(D0, 3, 0)>(vb); X[7] = tr_read<v_rd_off(D0, 3, 1)>(vb); } while (0)
; #define PVMMA(OD, X) do { OD = __builtin_amdgcn_mfma_f32_32x32x16_bf16(pa0, PVPK(X[0], X[1]), OD, 0, 0, 0); OD = __builtin_amdgcn_mfma_f32_32x32x16_bf16(pa1, PVPK(X[2], X[3]), OD, 0, 0, 0); \
;     OD = __builtin_amdgcn_mfma_f32_32x32x16_bf16(pa2, PVPK(X[4], X[5]), OD, 0, 0, 0); OD = __builtin_amdgcn_mfma_f32_32x32x16_bf16(pa3, PVPK(X[6], X[7]), OD, 0, 0, 0); } while (0)
; #define PVWAIT() do { asm volatile("s_waitcnt lgkmcnt(0)" ::: "memory"); SBAR(); } while (0)
; #define PVEXP(P, B, N) do { _Pragma("unroll") for (int r = (B); r < (B) + (N); ++r) P[r] = __builtin_amdgcn_exp2f(P[r]); } while (0)
; template <int NB> __device__ __forceinline__ void pv_blocks(f32x16* o, int vb, bf16x8 pa0, bf16x8 pa1, bf16x8 pa2, bf16x8 pa3, f32x16& pe0, f32x16& pe1) {
;     s16x4 x[8], y[8];
;     ...
;     PVLOAD(0, x); PVWAIT();
;     if (NB == 4) {
;         PVLOAD(1, y); SBAR(); PVMMA(o[0], x); PVEXP(pe0, 0, 8); SBAR(); PVWAIT();
;         PVLOAD(2, x); SBAR(); PVMMA(o[1], y); PVEXP(pe0, 8, 8); SBAR(); PVWAIT();
;         PVLOAD(3, y); SBAR(); PVMMA(o[2], x); PVEXP(pe1, 0, 8); SBAR(); PVWAIT();
;         PVMMA(o[3], y); PVEXP(pe1, 8, 8);
;     } else {
;         PVLOAD(1, y); SBAR(); PVMMA(o[0], x); PVEXP(pe0, 0, 16); SBAR(); PVWAIT();
;         PVMMA(o[1], y); PVEXP(pe1, 0, 16);
; template <int MODE>
; __device__ __forceinline__ void attn_unit(const UnitArgs& A, char* lds, const int wave_) {
;     ...
;             } else {
;                 const int c = 32 * (qb & 1) + r32; int cs = c - 8; cs = cs < 0 ? 0 : cs; cs = cs > 48 ? 48 : cs;
;                 const float* b = lutB + ((2 * A.h + half) * 15 + (kr - rq + 7)) * 128 + 64 + 4 * hi - c;
; #pragma unroll
;                 for (int r = 0; r < 16; ++r) { const int cc = (r & 3) + 8 * (r >> 2), j = 4 * hi + cc;
;                     p0[r] = ((unsigned)(j - cs) < 16u) ? p0[r] + b[cc] : NEG; p1[r] = ((unsigned)(j + 32 - cs) < 16u) ? p1[r] + b[32 + cc] : NEG; } }
	v_mov_b32_e32 v198, 0xf149f2ca
	v_mov_b32_e32 v179, 0xf149f2ca
	v_mov_b32_e32 v199, 0xf149f2ca
	v_mov_b32_e32 v180, 0xf149f2ca
	v_mov_b32_e32 v200, 0xf149f2ca
	v_mov_b32_e32 v181, 0xf149f2ca
	v_mov_b32_e32 v201, 0xf149f2ca
	v_mov_b32_e32 v185, 0xf149f2ca
	v_mov_b32_e32 v202, 0xf149f2ca
	v_mov_b32_e32 v186, 0xf149f2ca
	v_mov_b32_e32 v203, 0xf149f2ca
	v_mov_b32_e32 v187, 0xf149f2ca
	v_mov_b32_e32 v204, 0xf149f2ca
	v_mov_b32_e32 v188, 0xf149f2ca
	v_mov_b32_e32 v205, 0xf149f2ca
	v_mov_b32_e32 v189, 0xf149f2ca
	v_mov_b32_e32 v206, 0xf149f2ca
	v_mov_b32_e32 v190, 0xf149f2ca
	v_mov_b32_e32 v207, 0xf149f2ca
	v_mov_b32_e32 v191, 0xf149f2ca
	v_mov_b32_e32 v208, 0xf149f2ca
	v_mov_b32_e32 v192, 0xf149f2ca
	v_mov_b32_e32 v209, 0xf149f2ca
	v_mov_b32_e32 v193, 0xf149f2ca
	v_mov_b32_e32 v210, 0xf149f2ca
	v_mov_b32_e32 v194, 0xf149f2ca
	v_mov_b32_e32 v211, 0xf149f2ca
	v_mov_b32_e32 v195, 0xf149f2ca
	v_mov_b32_e32 v212, 0xf149f2ca
	v_mov_b32_e32 v196, 0xf149f2ca
	v_mov_b32_e32 v213, 0xf149f2ca
	v_mov_b32_e32 v197, 0xf149f2ca
	ds_read2_b32 v[246:247], v178 offset0:0 offset1:32
	ds_read2_b32 v[248:249], v178 offset0:1 offset1:33
	ds_read2_b32 v[250:251], v178 offset0:2 offset1:34
	ds_read2_b32 v[252:253], v178 offset0:3 offset1:35
	s_waitcnt lgkmcnt(0)
	s_mov_b64 exec, s[68:69]
	v_add_f32_e32 v179, v48, v246
	s_mov_b64 exec, s[4:5]
	v_add_f32_e32 v198, v32, v247
	s_mov_b64 exec, s[6:7]
	v_add_f32_e32 v180, v49, v248
	s_mov_b64 exec, s[8:9]
	v_add_f32_e32 v199, v33, v249
	s_mov_b64 exec, s[10:11]
	v_add_f32_e32 v181, v50, v250
	s_mov_b64 exec, s[12:13]
	v_add_f32_e32 v200, v34, v251
	s_mov_b64 exec, s[14:15]
	v_add_f32_e32 v185, v51, v252
	s_mov_b64 exec, s[16:17]
	v_add_f32_e32 v201, v35, v253
	s_mov_b64 exec, -1
	ds_read2_b32 v[246:247], v178 offset0:8 offset1:40
	ds_read2_b32 v[248:249], v178 offset0:9 offset1:41
	ds_read2_b32 v[250:251], v178 offset0:10 offset1:42
	ds_read2_b32 v[252:253], v178 offset0:11 offset1:43
	s_waitcnt lgkmcnt(0)
	s_mov_b64 exec, s[18:19]
	v_add_f32_e32 v186, v52, v246
	s_mov_b64 exec, s[20:21]
	v_add_f32_e32 v202, v36, v247
	s_mov_b64 exec, s[22:23]
	v_add_f32_e32 v187, v53, v248
	s_mov_b64 exec, s[24:25]
	v_add_f32_e32 v203, v37, v249
	s_mov_b64 exec, s[26:27]
	v_add_f32_e32 v188, v54, v250
	s_mov_b64 exec, s[28:29]
	v_add_f32_e32 v204, v38, v251
	s_mov_b64 exec, s[30:31]
	v_add_f32_e32 v189, v55, v252
	s_mov_b64 exec, s[34:35]
	v_add_f32_e32 v205, v39, v253
	s_mov_b64 exec, -1
	ds_read2_b32 v[246:247], v178 offset0:16 offset1:48
	ds_read2_b32 v[248:249], v178 offset0:17 offset1:49
	ds_read2_b32 v[250:251], v178 offset0:18 offset1:50
	ds_read2_b32 v[252:253], v178 offset0:19 offset1:51
	s_waitcnt lgkmcnt(0)
	s_mov_b64 exec, s[36:37]
	v_add_f32_e32 v190, v56, v246
	s_mov_b64 exec, s[38:39]
	v_add_f32_e32 v206, v40, v247
	s_mov_b64 exec, s[40:41]
	v_add_f32_e32 v191, v57, v248
	s_mov_b64 exec, s[42:43]
	v_add_f32_e32 v207, v41, v249
	s_mov_b64 exec, s[44:45]
	v_add_f32_e32 v192, v58, v250
	s_mov_b64 exec, s[46:47]
	v_add_f32_e32 v208, v42, v251
	s_mov_b64 exec, s[48:49]
	v_add_f32_e32 v193, v59, v252
	s_mov_b64 exec, s[50:51]
	v_add_f32_e32 v209, v43, v253
	s_mov_b64 exec, -1
	ds_read2_b32 v[246:247], v178 offset0:24 offset1:56
	ds_read2_b32 v[248:249], v178 offset0:25 offset1:57
	ds_read2_b32 v[250:251], v178 offset0:26 offset1:58
	ds_read2_b32 v[252:253], v178 offset0:27 offset1:59
	s_waitcnt lgkmcnt(0)
	s_mov_b64 exec, s[52:53]
	v_add_f32_e32 v194, v60, v246
	s_mov_b64 exec, s[54:55]
	v_add_f32_e32 v210, v44, v247
	s_mov_b64 exec, s[56:57]
	v_add_f32_e32 v195, v61, v248
	s_mov_b64 exec, s[58:59]
	v_add_f32_e32 v211, v45, v249
	s_mov_b64 exec, s[60:61]
	v_add_f32_e32 v196, v62, v250
	s_mov_b64 exec, s[62:63]
	v_add_f32_e32 v212, v46, v251
	s_mov_b64 exec, s[64:65]
	v_add_f32_e32 v197, v63, v252
	s_mov_b64 exec, s[66:67]
	v_add_f32_e32 v213, v47, v253
	s_mov_b64 exec, -1
	s_mov_b64 vcc, -1
.LBB0_488:
	ds_read_b64_tr_b16 v[32:33], v111 offset:0
	ds_read_b64_tr_b16 v[34:35], v111 offset:0x800
	ds_read_b64_tr_b16 v[36:37], v111 offset:0x1000
	ds_read_b64_tr_b16 v[38:39], v111 offset:0x1800
	ds_read_b64_tr_b16 v[40:41], v111 offset:0x2000
	ds_read_b64_tr_b16 v[42:43], v111 offset:0x2800
	ds_read_b64_tr_b16 v[44:45], v111 offset:0x3000
	ds_read_b64_tr_b16 v[46:47], v111 offset:0x3800
	s_waitcnt lgkmcnt(0)
	ds_read_b64_tr_b16 v[48:49], v111 offset:0x200
	ds_read_b64_tr_b16 v[50:51], v111 offset:0xa00
	ds_read_b64_tr_b16 v[52:53], v111 offset:0x1200
	ds_read_b64_tr_b16 v[54:55], v111 offset:0x1a00
	ds_read_b64_tr_b16 v[56:57], v111 offset:0x2200
	ds_read_b64_tr_b16 v[58:59], v111 offset:0x2a00
	ds_read_b64_tr_b16 v[60:61], v111 offset:0x3200
	ds_read_b64_tr_b16 v[62:63], v111 offset:0x3a00
	s_nop 0
	v_mfma_f32_32x32x16_bf16 v[16:31], v[64:67], v[32:35], v[16:31]
	v_exp_f32_e32 v179, v179
	v_exp_f32_e32 v180, v180
	v_exp_f32_e32 v181, v181
	v_exp_f32_e32 v185, v185
	v_exp_f32_e32 v186, v186
	v_exp_f32_e32 v187, v187
	v_exp_f32_e32 v188, v188
	v_mfma_f32_32x32x16_bf16 v[16:31], v[76:79], v[36:39], v[16:31]
	v_exp_f32_e32 v189, v189
	v_exp_f32_e32 v190, v190
	v_exp_f32_e32 v191, v191
	v_exp_f32_e32 v192, v192
	v_exp_f32_e32 v193, v193
	v_exp_f32_e32 v194, v194
	v_exp_f32_e32 v195, v195
	v_mfma_f32_32x32x16_bf16 v[16:31], v[96:99], v[40:43], v[16:31]
	v_exp_f32_e32 v196, v196
	v_exp_f32_e32 v197, v197
	v_mfma_f32_32x32x16_bf16 v[16:31], v[100:103], v[44:47], v[16:31]
	s_waitcnt lgkmcnt(0)
	v_mfma_f32_32x32x16_bf16 v[0:15], v[64:67], v[48:51], v[0:15]
	v_exp_f32_e32 v198, v198
	v_exp_f32_e32 v199, v199
	v_exp_f32_e32 v200, v200
	v_exp_f32_e32 v201, v201
	v_exp_f32_e32 v202, v202
	v_exp_f32_e32 v203, v203
	v_exp_f32_e32 v204, v204
	v_mfma_f32_32x32x16_bf16 v[0:15], v[76:79], v[52:55], v[0:15]
	v_exp_f32_e32 v205, v205
	v_exp_f32_e32 v206, v206
	v_exp_f32_e32 v207, v207
	v_exp_f32_e32 v208, v208
	v_exp_f32_e32 v209, v209
	v_exp_f32_e32 v210, v210
	v_exp_f32_e32 v211, v211
	v_mfma_f32_32x32x16_bf16 v[0:15], v[96:99], v[56:59], v[0:15]
	v_exp_f32_e32 v212, v212
	v_exp_f32_e32 v213, v213
	s_barrier
; #define SBAR() __builtin_amdgcn_sched_barrier(0)
; #define SWRITE(b, i) do { *(bf16x8*)(V_lds + (b) * (int)SHM_V + vst0) = sr_[i].vs0; *(bf16x8*)(V_lds + (b) * (int)SHM_V + vst0 + 8192) = sr_[i].vs1; } while (0)
; #define SWAIT() asm volatile("s_waitcnt vmcnt(0)" ::: "memory")
; #define QK(P0, P1, KS, t) do { float v_ = -A.mshift; if (MODE == 0) { const int z_ = zone_of(t); v_ += (z_ == 0 ? A.farL : (z_ == 2 ? A.farR : 0.f)); } \
;     qkt(P0, P1, KS, qr, v_, r32, hi, half); } while (0)
; template <int MODE>
; __device__ __forceinline__ void attn_unit(const UnitArgs& A, char* lds, const int wave_) {
;     ...
;     for (int j = 1; j + 1 < NT; j += 2) {
;         SBAR(); QK(pB0, pB1, K_lds + SHM_K, j);
;         finishSM(pA0, pA1, l_reg, pa0, pa1, pa2, pa3); SBAR();
;         SLOAD(0, j + 1); SBAR();
;         post(pB0, pB1, j); PV(0, pB0, pB1);
;         __syncthreads(); SWAIT(); SWRITE(0, 0);
;         __syncthreads();
;         SBAR(); QK(pA0, pA1, K_lds, j + 1);
;         finishSM(pB0, pB1, l_reg, pa0, pa1, pa2, pa3); SBAR();
;         SLOAD(0, j + 2); SBAR();
;         post(pA0, pA1, j + 1); PV(1, pA0, pA1);
;         __syncthreads(); SWAIT(); SWRITE(1, 0);
	s_waitcnt vmcnt(0)
	s_waitcnt vmcnt(1)
	ds_write_b128 v158, v[68:71]
	s_waitcnt vmcnt(0)
	ds_write_b128 v158, v[72:75] offset:8192
	v_mfma_f32_32x32x16_bf16 v[0:15], v[100:103], v[60:63], v[0:15]
	s_waitcnt lgkmcnt(0)
	s_barrier
	ds_read_b128 v[32:35], v113 offset:32768
	ds_read_b128 v[96:99], v113 offset:40960
	ds_read_b128 v[100:103], v114 offset:32768
	ds_read_b128 v[214:217], v114 offset:40960
	v_readlane_b32 s72, v255, 10
	v_readlane_b32 s73, v255, 11
	v_readlane_b32 s74, v255, 12
	v_readlane_b32 s75, v255, 13
	v_readlane_b32 s76, v255, 14
	v_readlane_b32 s77, v255, 15
	v_readlane_b32 s78, v255, 16
	v_readlane_b32 s79, v255, 17
	v_readlane_b32 s80, v255, 18
	v_readlane_b32 s81, v255, 19
	v_readlane_b32 s82, v255, 20
	v_readlane_b32 s83, v255, 21
	v_readlane_b32 s84, v255, 22
	v_readlane_b32 s85, v255, 23
	v_readlane_b32 s86, v255, 24
	v_readlane_b32 s87, v255, 25
	v_mov_b64_e32 v[64:65], s[72:73]
	v_mov_b64_e32 v[66:67], s[74:75]
	v_mov_b64_e32 v[68:69], s[76:77]
	v_mov_b64_e32 v[70:71], s[78:79]
	v_mov_b64_e32 v[72:73], s[80:81]
	v_mov_b64_e32 v[74:75], s[82:83]
	v_mov_b64_e32 v[76:77], s[84:85]
	v_mov_b64_e32 v[78:79], s[86:87]
	s_waitcnt lgkmcnt(3)
	s_nop 0
	v_mfma_f32_32x32x16_bf16 v[48:63], v[32:35], v[92:95], v[64:79]
	s_waitcnt lgkmcnt(2)
	v_mfma_f32_32x32x16_bf16 v[32:47], v[96:99], v[92:95], v[64:79]
	s_nop 6
	ds_read_b128 v[64:67], v115 offset:32768
	ds_read_b128 v[68:71], v115 offset:40960
	s_waitcnt lgkmcnt(3)
	v_mfma_f32_32x32x16_bf16 v[48:63], v[100:103], v[88:91], v[48:63]
	ds_read_b128 v[72:75], v116 offset:32768
	ds_read_b128 v[76:79], v116 offset:40960
	s_waitcnt lgkmcnt(4)
	v_mfma_f32_32x32x16_bf16 v[32:47], v[214:217], v[88:91], v[32:47]
	s_waitcnt lgkmcnt(3)
	v_mfma_f32_32x32x16_bf16 v[48:63], v[64:67], v[84:87], v[48:63]
	v_cvt_pk_bf16_f32 v64, v179, v180
	v_cvt_pk_bf16_f32 v65, v181, v185
	v_cvt_pk_bf16_f32 v66, v186, v187
	v_cvt_pk_bf16_f32 v67, v188, v189
	v_cvt_pk_bf16_f32 v96, v198, v199
	v_cvt_pk_bf16_f32 v97, v200, v201
	v_cvt_pk_bf16_f32 v98, v202, v203
	s_waitcnt lgkmcnt(2)
	v_mfma_f32_32x32x16_bf16 v[32:47], v[68:71], v[84:87], v[32:47]
	v_cvt_pk_bf16_f32 v99, v204, v205
	v_cvt_pk_bf16_f32 v100, v206, v207
	v_cvt_pk_bf16_f32 v101, v208, v209
	v_cvt_pk_bf16_f32 v102, v210, v211
	v_cvt_pk_bf16_f32 v103, v212, v213
	v_permlane32_swap_b32_e32 v64, v66
	s_waitcnt lgkmcnt(1)
	v_mfma_f32_32x32x16_bf16 v[48:63], v[72:75], v[80:83], v[48:63]
	v_permlane32_swap_b32_e32 v65, v67
	v_permlane32_swap_b32_e32 v96, v98
	v_permlane32_swap_b32_e32 v97, v99
	v_permlane32_swap_b32_e32 v100, v102
	s_waitcnt lgkmcnt(0)
	v_mfma_f32_32x32x16_bf16 v[32:47], v[76:79], v[80:83], v[32:47]
	v_cvt_pk_bf16_f32 v76, v190, v191
	v_cvt_pk_bf16_f32 v77, v192, v193
	v_cvt_pk_bf16_f32 v78, v194, v195
	v_cvt_pk_bf16_f32 v79, v196, v197
	s_nop 0
	v_permlane32_swap_b32_e32 v76, v78
	v_permlane32_swap_b32_e32 v77, v79
	v_permlane32_swap_b32_e32 v101, v103
	s_add_i32 s1, s1, 3
	s_min_i32 s1, s1, s71
	s_lshl_b32 s72, s1, 6
	s_mul_i32 s1, s1, 0x50000
	s_mul_hi_i32 s75, s72, 0x1400
	s_add_u32 s72, s33, s1
	s_addc_u32 s73, s92, s75
	s_add_u32 s74, s89, s1
	s_addc_u32 s75, s2, s75
	v_lshl_add_u64 v[68:69], s[74:75], 0, v[144:145]
	s_mov_b32 s74, 0x28000
	v_add_co_u32_e32 v72, vcc, s74, v68
	s_add_i32 s1, s96, 0xffffc000
	s_nop 0
	v_addc_co_u32_e32 v73, vcc, 0, v69, vcc
	global_load_dwordx4 v[68:71], v[68:69], off
	s_nop 0
	global_load_dwordx4 v[72:75], v[72:73], off
	s_and_b32 s1, s1, 0x4000
	v_lshl_add_u64 v[182:183], s[72:73], 0, v[104:105]
	s_mov_b64 s[72:73], 0xe00
	s_add_i32 s1, s1, s70
	v_lshl_add_u64 v[214:215], v[182:183], 0, s[72:73]
	s_mov_b32 s72, m0
	s_mov_b32 m0, s1
	s_nop 0
	global_load_lds_dwordx4 v[214:215], off
	s_mov_b32 m0, s72
	s_mov_b64 s[72:73], 0x28e00
	v_lshl_add_u64 v[182:183], v[182:183], 0, s[72:73]
	s_addk_i32 s1, 0x2000
	s_mov_b32 s72, m0
	s_mov_b32 m0, s1
	s_nop 0
	global_load_lds_dwordx4 v[182:183], off
	s_mov_b32 m0, s72
	s_cmp_ge_i32 s0, s3
	s_cselect_b64 s[72:73], -1, 0
	s_cmp_lt_i32 s0, s91
	s_cselect_b64 s[0:1], -1, 0
	s_and_b64 s[0:1], s[72:73], s[0:1]
	v_mov_b32_e32 v245, 0xf149f2ca
	s_andn2_b64 vcc, exec, s[0:1]
	v_mov_b32_e32 v244, 0xf149f2ca
	v_mov_b32_e32 v242, 0xf149f2ca
	v_mov_b32_e32 v241, 0xf149f2ca
	v_mov_b32_e32 v239, 0xf149f2ca
	v_mov_b32_e32 v236, 0xf149f2ca
	v_mov_b32_e32 v234, 0xf149f2ca
	v_mov_b32_e32 v232, 0xf149f2ca
	v_mov_b32_e32 v231, 0xf149f2ca
	v_mov_b32_e32 v229, 0xf149f2ca
	v_mov_b32_e32 v227, 0xf149f2ca
	v_mov_b32_e32 v225, 0xf149f2ca
	v_mov_b32_e32 v222, 0xf149f2ca
	v_mov_b32_e32 v220, 0xf149f2ca
	v_mov_b32_e32 v218, 0xf149f2ca
	v_mov_b32_e32 v216, 0xf149f2ca
	v_mov_b32_e32 v240, 0xf149f2ca
	v_mov_b32_e32 v238, 0xf149f2ca
	v_mov_b32_e32 v237, 0xf149f2ca
	v_mov_b32_e32 v235, 0xf149f2ca
	v_mov_b32_e32 v233, 0xf149f2ca
	v_mov_b32_e32 v230, 0xf149f2ca
	v_mov_b32_e32 v228, 0xf149f2ca
	v_mov_b32_e32 v226, 0xf149f2ca
	v_mov_b32_e32 v224, 0xf149f2ca
	v_mov_b32_e32 v223, 0xf149f2ca
	v_mov_b32_e32 v221, 0xf149f2ca
	v_mov_b32_e32 v219, 0xf149f2ca
	v_mov_b32_e32 v217, 0xf149f2ca
	v_mov_b32_e32 v215, 0xf149f2ca
	v_mov_b32_e32 v214, 0xf149f2ca
	v_mov_b32_e32 v243, 0xf149f2ca
	s_cbranch_vccnz .LBB0_554
; template <int MODE>
; __device__ __forceinline__ void attn_unit(const UnitArgs& A, char* lds, const int wave_) {
;     ...
;             } else {
;                 const int c = 32 * (qb & 1) + r32; int cs = c - 8; cs = cs < 0 ? 0 : cs; cs = cs > 48 ? 48 : cs;
;                 const float* b = lutB + ((2 * A.h + half) * 15 + (kr - rq + 7)) * 128 + 64 + 4 * hi - c;
; #pragma unroll
;                 for (int r = 0; r < 16; ++r) { const int cc = (r & 3) + 8 * (r >> 2), j = 4 * hi + cc;
;                     p0[r] = ((unsigned)(j - cs) < 16u) ? p0[r] + b[cc] : NEG; p1[r] = ((unsigned)(j + 32 - cs) < 16u) ? p1[r] + b[32 + cc] : NEG; } }
	v_mov_b32_e32 v214, 0xf149f2ca
	v_mov_b32_e32 v216, 0xf149f2ca
	v_mov_b32_e32 v215, 0xf149f2ca
	v_mov_b32_e32 v218, 0xf149f2ca
	v_mov_b32_e32 v217, 0xf149f2ca
	v_mov_b32_e32 v220, 0xf149f2ca
	v_mov_b32_e32 v219, 0xf149f2ca
	v_mov_b32_e32 v222, 0xf149f2ca
	v_mov_b32_e32 v221, 0xf149f2ca
	v_mov_b32_e32 v225, 0xf149f2ca
	v_mov_b32_e32 v223, 0xf149f2ca
	v_mov_b32_e32 v227, 0xf149f2ca
	v_mov_b32_e32 v224, 0xf149f2ca
	v_mov_b32_e32 v229, 0xf149f2ca
	v_mov_b32_e32 v226, 0xf149f2ca
	v_mov_b32_e32 v231, 0xf149f2ca
	v_mov_b32_e32 v228, 0xf149f2ca
	v_mov_b32_e32 v232, 0xf149f2ca
	v_mov_b32_e32 v230, 0xf149f2ca
	v_mov_b32_e32 v234, 0xf149f2ca
	v_mov_b32_e32 v233, 0xf149f2ca
	v_mov_b32_e32 v236, 0xf149f2ca
	v_mov_b32_e32 v235, 0xf149f2ca
	v_mov_b32_e32 v239, 0xf149f2ca
	v_mov_b32_e32 v237, 0xf149f2ca
	v_mov_b32_e32 v241, 0xf149f2ca
	v_mov_b32_e32 v238, 0xf149f2ca
	v_mov_b32_e32 v242, 0xf149f2ca
	v_mov_b32_e32 v240, 0xf149f2ca
	v_mov_b32_e32 v244, 0xf149f2ca
	v_mov_b32_e32 v243, 0xf149f2ca
	v_mov_b32_e32 v245, 0xf149f2ca
	ds_read2_b32 v[246:247], v178 offset0:128 offset1:160
	ds_read2_b32 v[248:249], v178 offset0:129 offset1:161
	ds_read2_b32 v[250:251], v178 offset0:130 offset1:162
	ds_read2_b32 v[252:253], v178 offset0:131 offset1:163
	s_waitcnt lgkmcnt(0)
	s_mov_b64 exec, s[68:69]
	v_add_f32_e32 v216, v48, v246
	s_mov_b64 exec, s[4:5]
	v_add_f32_e32 v214, v32, v247
	s_mov_b64 exec, s[6:7]
	v_add_f32_e32 v218, v49, v248
	s_mov_b64 exec, s[8:9]
	v_add_f32_e32 v215, v33, v249
	s_mov_b64 exec, s[10:11]
	v_add_f32_e32 v220, v50, v250
	s_mov_b64 exec, s[12:13]
	v_add_f32_e32 v217, v34, v251
	s_mov_b64 exec, s[14:15]
	v_add_f32_e32 v222, v51, v252
	s_mov_b64 exec, s[16:17]
	v_add_f32_e32 v219, v35, v253
	s_mov_b64 exec, -1
	ds_read2_b32 v[246:247], v178 offset0:136 offset1:168
	ds_read2_b32 v[248:249], v178 offset0:137 offset1:169
	ds_read2_b32 v[250:251], v178 offset0:138 offset1:170
	ds_read2_b32 v[252:253], v178 offset0:139 offset1:171
	s_waitcnt lgkmcnt(0)
	s_mov_b64 exec, s[18:19]
	v_add_f32_e32 v225, v52, v246
	s_mov_b64 exec, s[20:21]
	v_add_f32_e32 v221, v36, v247
	s_mov_b64 exec, s[22:23]
	v_add_f32_e32 v227, v53, v248
	s_mov_b64 exec, s[24:25]
	v_add_f32_e32 v223, v37, v249
	s_mov_b64 exec, s[26:27]
	v_add_f32_e32 v229, v54, v250
	s_mov_b64 exec, s[28:29]
	v_add_f32_e32 v224, v38, v251
	s_mov_b64 exec, s[30:31]
	v_add_f32_e32 v231, v55, v252
	s_mov_b64 exec, s[34:35]
	v_add_f32_e32 v226, v39, v253
	s_mov_b64 exec, -1
	ds_read2_b32 v[246:247], v178 offset0:144 offset1:176
	ds_read2_b32 v[248:249], v178 offset0:145 offset1:177
	ds_read2_b32 v[250:251], v178 offset0:146 offset1:178
	ds_read2_b32 v[252:253], v178 offset0:147 offset1:179
	s_waitcnt lgkmcnt(0)
	s_mov_b64 exec, s[36:37]
	v_add_f32_e32 v232, v56, v246
	s_mov_b64 exec, s[38:39]
	v_add_f32_e32 v228, v40, v247
	s_mov_b64 exec, s[40:41]
	v_add_f32_e32 v234, v57, v248
	s_mov_b64 exec, s[42:43]
	v_add_f32_e32 v230, v41, v249
	s_mov_b64 exec, s[44:45]
	v_add_f32_e32 v236, v58, v250
	s_mov_b64 exec, s[46:47]
	v_add_f32_e32 v233, v42, v251
	s_mov_b64 exec, s[48:49]
	v_add_f32_e32 v239, v59, v252
	s_mov_b64 exec, s[50:51]
	v_add_f32_e32 v235, v43, v253
	s_mov_b64 exec, -1
	ds_read2_b32 v[246:247], v178 offset0:152 offset1:184
	ds_read2_b32 v[248:249], v178 offset0:153 offset1:185
	ds_read2_b32 v[250:251], v178 offset0:154 offset1:186
	ds_read2_b32 v[252:253], v178 offset0:155 offset1:187
	s_waitcnt lgkmcnt(0)
	s_mov_b64 exec, s[52:53]
	v_add_f32_e32 v241, v60, v246
	s_mov_b64 exec, s[54:55]
	v_add_f32_e32 v237, v44, v247
	s_mov_b64 exec, s[56:57]
	v_add_f32_e32 v242, v61, v248
	s_mov_b64 exec, s[58:59]
	v_add_f32_e32 v238, v45, v249
	s_mov_b64 exec, s[60:61]
	v_add_f32_e32 v244, v62, v250
	s_mov_b64 exec, s[62:63]
	v_add_f32_e32 v240, v46, v251
	s_mov_b64 exec, s[64:65]
	v_add_f32_e32 v245, v63, v252
	s_mov_b64 exec, s[66:67]
	v_add_f32_e32 v243, v47, v253
	s_mov_b64 exec, -1
	s_mov_b64 vcc, -1
